# back-edge rotation on both GEMM K-loops (P1 and P4): loop-carried scalar updates moved into the last MFMA block's shadow
# speedup vs baseline: 1.0038x; 1.0038x over previous
.LBB0_661:
	v_add_u32_e32 v149, s42, v147
	ds_read_b128 v[150:153], v149
	ds_read_b128 v[154:157], v149 offset:1024
	ds_read_b128 v[158:161], v149 offset:2048
	ds_read_b128 v[162:165], v149 offset:3072
	v_add_u32_e32 v149, s43, v147
	s_add_u32 s24, s10, s22
	ds_read_b128 v[170:173], v149
	ds_read_b128 v[174:177], v149 offset:1024
	ds_read_b128 v[178:181], v149 offset:2048
	ds_read_b128 v[182:185], v149 offset:3072
	s_addc_u32 s25, s11, s23
	s_add_u32 s24, s24, 0x100
	s_addc_u32 s25, s25, 0
	s_add_u32 s52, s47, s22
	s_addc_u32 s53, s48, s23
	s_cmpk_eq_i32 s22, 0xf00
	s_cselect_b32 s27, s17, s25
	s_cselect_b32 s26, s49, s24
	s_cselect_b32 s25, s15, s53
	s_cselect_b32 s24, s50, s52
	v_lshl_add_u64 v[166:167], v[140:141], 0, s[22:23]
	s_add_i32 m0, s29, 0xc000
	ds_read_b128 v[186:189], v148
	ds_read_b128 v[190:193], v148 offset:1024
	ds_read_b128 v[194:197], v148 offset:2048
	ds_read_b128 v[198:201], v148 offset:3072
	ds_read_b128 v[202:205], v148 offset:4096
	ds_read_b128 v[206:209], v148 offset:5120
	ds_read_b128 v[210:213], v148 offset:6144
	ds_read_b128 v[214:217], v148 offset:7168
	global_load_lds_dwordx4 v[166:167], off
	v_lshl_add_u64 v[166:167], v[142:143], 0, s[22:23]
	s_add_i32 m0, s29, 0xe000
	s_nop 0
	global_load_lds_dwordx4 v[166:167], off
	s_waitcnt vmcnt(8)
	s_waitcnt lgkmcnt(0)
	s_barrier
	s_setprio 1
	s_waitcnt lgkmcnt(0)
	v_mfma_f32_16x16x32_bf16 v[124:127], v[150:153], v[186:189], v[124:127]
	v_mfma_f32_16x16x32_bf16 v[120:123], v[158:161], v[186:189], v[120:123]
	v_mfma_f32_16x16x32_bf16 v[108:111], v[150:153], v[194:197], v[108:111]
	v_mfma_f32_16x16x32_bf16 v[104:107], v[158:161], v[194:197], v[104:107]
	v_mfma_f32_16x16x32_bf16 v[92:95], v[150:153], v[202:205], v[92:95]
	v_mfma_f32_16x16x32_bf16 v[88:91], v[158:161], v[202:205], v[88:91]
	v_mfma_f32_16x16x32_bf16 v[76:79], v[150:153], v[210:213], v[76:79]
	v_mfma_f32_16x16x32_bf16 v[72:75], v[158:161], v[210:213], v[72:75]
	v_mfma_f32_16x16x32_bf16 v[124:127], v[154:157], v[190:193], v[124:127]
	v_mfma_f32_16x16x32_bf16 v[120:123], v[162:165], v[190:193], v[120:123]
	v_mfma_f32_16x16x32_bf16 v[108:111], v[154:157], v[198:201], v[108:111]
	v_mfma_f32_16x16x32_bf16 v[104:107], v[162:165], v[198:201], v[104:107]
	v_mfma_f32_16x16x32_bf16 v[92:95], v[154:157], v[206:209], v[92:95]
	v_mfma_f32_16x16x32_bf16 v[88:91], v[162:165], v[206:209], v[88:91]
	v_mfma_f32_16x16x32_bf16 v[76:79], v[154:157], v[214:217], v[76:79]
	v_mfma_f32_16x16x32_bf16 v[72:75], v[162:165], v[214:217], v[72:75]
	s_setprio 0
	s_setprio 1
	v_mfma_f32_16x16x32_bf16 v[116:119], v[170:173], v[186:189], v[116:119]
	v_mfma_f32_16x16x32_bf16 v[112:115], v[178:181], v[186:189], v[112:115]
	v_mfma_f32_16x16x32_bf16 v[100:103], v[170:173], v[194:197], v[100:103]
	v_mfma_f32_16x16x32_bf16 v[96:99], v[178:181], v[194:197], v[96:99]
	v_mfma_f32_16x16x32_bf16 v[84:87], v[170:173], v[202:205], v[84:87]
	v_mfma_f32_16x16x32_bf16 v[80:83], v[178:181], v[202:205], v[80:83]
	v_mfma_f32_16x16x32_bf16 v[68:71], v[170:173], v[210:213], v[68:71]
	v_mfma_f32_16x16x32_bf16 v[64:67], v[178:181], v[210:213], v[64:67]
	v_mfma_f32_16x16x32_bf16 v[116:119], v[174:177], v[190:193], v[116:119]
	v_mfma_f32_16x16x32_bf16 v[112:115], v[182:185], v[190:193], v[112:115]
	v_mfma_f32_16x16x32_bf16 v[100:103], v[174:177], v[198:201], v[100:103]
	v_mfma_f32_16x16x32_bf16 v[96:99], v[182:185], v[198:201], v[96:99]
	v_mfma_f32_16x16x32_bf16 v[84:87], v[174:177], v[206:209], v[84:87]
	v_mfma_f32_16x16x32_bf16 v[80:83], v[182:185], v[206:209], v[80:83]
	v_mfma_f32_16x16x32_bf16 v[68:71], v[174:177], v[214:217], v[68:71]
	v_mfma_f32_16x16x32_bf16 v[64:67], v[182:185], v[214:217], v[64:67]
	s_setprio 0
	s_barrier
	s_add_i32 s52, s42, s9
	v_lshl_add_u64 v[166:167], s[24:25], 0, v[130:131]
	s_mov_b32 m0, s52
	ds_read_b128 v[186:189], v148 offset:16384
	ds_read_b128 v[190:193], v148 offset:17408
	ds_read_b128 v[194:197], v148 offset:18432
	ds_read_b128 v[198:201], v148 offset:19456
	ds_read_b128 v[202:205], v148 offset:20480
	ds_read_b128 v[206:209], v148 offset:21504
	ds_read_b128 v[210:213], v148 offset:22528
	ds_read_b128 v[214:217], v148 offset:23552
	global_load_lds_dwordx4 v[166:167], off
	s_add_i32 m0, s52, 0x2000
	s_add_u32 s52, s24, 0x80000
	v_lshl_add_u64 v[218:219], s[24:25], 0, v[128:129]
	s_addc_u32 s53, s25, 0
	s_add_i32 s54, s43, s9
	global_load_lds_dwordx4 v[218:219], off
	v_lshl_add_u64 v[220:221], s[52:53], 0, v[130:131]
	s_mov_b32 m0, s54
	v_lshl_add_u64 v[222:223], s[26:27], 0, v[128:129]
	global_load_lds_dwordx4 v[220:221], off
	v_lshl_add_u64 v[220:221], s[52:53], 0, v[128:129]
	s_add_i32 m0, s54, 0x2000
	s_nop 0
	global_load_lds_dwordx4 v[220:221], off
	v_lshl_add_u64 v[220:221], s[26:27], 0, v[130:131]
	s_mov_b32 m0, s29
	s_nop 0
	global_load_lds_dwordx4 v[220:221], off
	s_mov_b32 m0, s33
	s_nop 0
	global_load_lds_dwordx4 v[222:223], off
	s_waitcnt vmcnt(8)
	s_waitcnt lgkmcnt(0)
	s_barrier
	s_setprio 1
	s_waitcnt lgkmcnt(0)
	v_mfma_f32_16x16x32_bf16 v[60:63], v[150:153], v[186:189], v[60:63]
	v_mfma_f32_16x16x32_bf16 v[56:59], v[158:161], v[186:189], v[56:59]
	v_mfma_f32_16x16x32_bf16 v[44:47], v[150:153], v[194:197], v[44:47]
	v_mfma_f32_16x16x32_bf16 v[40:43], v[158:161], v[194:197], v[40:43]
	v_mfma_f32_16x16x32_bf16 v[28:31], v[150:153], v[202:205], v[28:31]
	v_mfma_f32_16x16x32_bf16 v[24:27], v[158:161], v[202:205], v[24:27]
	v_mfma_f32_16x16x32_bf16 v[12:15], v[150:153], v[210:213], v[12:15]
	v_mfma_f32_16x16x32_bf16 v[8:11], v[158:161], v[210:213], v[8:11]
	v_mfma_f32_16x16x32_bf16 v[60:63], v[154:157], v[190:193], v[60:63]
	v_mfma_f32_16x16x32_bf16 v[56:59], v[162:165], v[190:193], v[56:59]
	v_mfma_f32_16x16x32_bf16 v[44:47], v[154:157], v[198:201], v[44:47]
	v_mfma_f32_16x16x32_bf16 v[40:43], v[162:165], v[198:201], v[40:43]
	v_mfma_f32_16x16x32_bf16 v[28:31], v[154:157], v[206:209], v[28:31]
	v_mfma_f32_16x16x32_bf16 v[24:27], v[162:165], v[206:209], v[24:27]
	v_mfma_f32_16x16x32_bf16 v[12:15], v[154:157], v[214:217], v[12:15]
	v_mfma_f32_16x16x32_bf16 v[8:11], v[162:165], v[214:217], v[8:11]
	s_setprio 0
	s_setprio 1
	v_mfma_f32_16x16x32_bf16 v[52:55], v[170:173], v[186:189], v[52:55]
	v_mfma_f32_16x16x32_bf16 v[48:51], v[178:181], v[186:189], v[48:51]
	v_mfma_f32_16x16x32_bf16 v[36:39], v[170:173], v[194:197], v[36:39]
	v_mfma_f32_16x16x32_bf16 v[32:35], v[178:181], v[194:197], v[32:35]
	v_mfma_f32_16x16x32_bf16 v[20:23], v[170:173], v[202:205], v[20:23]
	v_mfma_f32_16x16x32_bf16 v[16:19], v[178:181], v[202:205], v[16:19]
	v_mfma_f32_16x16x32_bf16 v[4:7], v[170:173], v[210:213], v[4:7]
	v_mfma_f32_16x16x32_bf16 v[0:3], v[178:181], v[210:213], v[0:3]
	v_mfma_f32_16x16x32_bf16 v[52:55], v[174:177], v[190:193], v[52:55]
	v_mfma_f32_16x16x32_bf16 v[48:51], v[182:185], v[190:193], v[48:51]
	v_mfma_f32_16x16x32_bf16 v[36:39], v[174:177], v[198:201], v[36:39]
	v_mfma_f32_16x16x32_bf16 v[32:35], v[182:185], v[198:201], v[32:35]
	v_mfma_f32_16x16x32_bf16 v[20:23], v[174:177], v[206:209], v[20:23]
	v_mfma_f32_16x16x32_bf16 v[16:19], v[182:185], v[206:209], v[16:19]
	v_mfma_f32_16x16x32_bf16 v[4:7], v[174:177], v[214:217], v[4:7]
	v_mfma_f32_16x16x32_bf16 v[0:3], v[182:185], v[214:217], v[0:3]
	s_setprio 0
	s_barrier
	s_add_i32 s52, 0, 0x18000
	v_add_u32_e32 v149, s52, v147
	s_add_i32 s53, 0, 0x1c000
	ds_read_b128 v[150:153], v149
	ds_read_b128 v[154:157], v149 offset:1024
	ds_read_b128 v[158:161], v149 offset:2048
	ds_read_b128 v[162:165], v149 offset:3072
	v_add_u32_e32 v149, s53, v147
	ds_read_b128 v[170:173], v149
	ds_read_b128 v[174:177], v149 offset:1024
	ds_read_b128 v[178:181], v149 offset:2048
	ds_read_b128 v[182:185], v149 offset:3072
	s_add_u32 s26, s26, 0x80000
	s_addc_u32 s27, s27, 0
	s_mov_b32 m0, s36
	v_lshl_add_u64 v[224:225], s[26:27], 0, v[130:131]
	ds_read_b128 v[186:189], v148 offset:32768
	ds_read_b128 v[190:193], v148 offset:33792
	ds_read_b128 v[194:197], v148 offset:34816
	ds_read_b128 v[198:201], v148 offset:35840
	ds_read_b128 v[202:205], v148 offset:36864
	ds_read_b128 v[206:209], v148 offset:37888
	ds_read_b128 v[210:213], v148 offset:38912
	ds_read_b128 v[214:217], v148 offset:39936
	global_load_lds_dwordx4 v[224:225], off
	v_lshl_add_u64 v[224:225], s[26:27], 0, v[128:129]
	s_mov_b32 m0, s37
	s_nop 0
	global_load_lds_dwordx4 v[224:225], off
	s_waitcnt vmcnt(8)
	s_waitcnt lgkmcnt(0)
	s_barrier
	s_setprio 1
	s_waitcnt lgkmcnt(0)
	v_mfma_f32_16x16x32_bf16 v[124:127], v[150:153], v[186:189], v[124:127]
	v_mfma_f32_16x16x32_bf16 v[120:123], v[158:161], v[186:189], v[120:123]
	v_mfma_f32_16x16x32_bf16 v[108:111], v[150:153], v[194:197], v[108:111]
	v_mfma_f32_16x16x32_bf16 v[104:107], v[158:161], v[194:197], v[104:107]
	v_mfma_f32_16x16x32_bf16 v[92:95], v[150:153], v[202:205], v[92:95]
	v_mfma_f32_16x16x32_bf16 v[88:91], v[158:161], v[202:205], v[88:91]
	v_mfma_f32_16x16x32_bf16 v[76:79], v[150:153], v[210:213], v[76:79]
	v_mfma_f32_16x16x32_bf16 v[72:75], v[158:161], v[210:213], v[72:75]
	v_mfma_f32_16x16x32_bf16 v[124:127], v[154:157], v[190:193], v[124:127]
	v_mfma_f32_16x16x32_bf16 v[120:123], v[162:165], v[190:193], v[120:123]
	v_mfma_f32_16x16x32_bf16 v[108:111], v[154:157], v[198:201], v[108:111]
	v_mfma_f32_16x16x32_bf16 v[104:107], v[162:165], v[198:201], v[104:107]
	v_mfma_f32_16x16x32_bf16 v[92:95], v[154:157], v[206:209], v[92:95]
	v_mfma_f32_16x16x32_bf16 v[88:91], v[162:165], v[206:209], v[88:91]
	v_mfma_f32_16x16x32_bf16 v[76:79], v[154:157], v[214:217], v[76:79]
	v_mfma_f32_16x16x32_bf16 v[72:75], v[162:165], v[214:217], v[72:75]
	s_setprio 0
	s_setprio 1
	v_mfma_f32_16x16x32_bf16 v[116:119], v[170:173], v[186:189], v[116:119]
	v_mfma_f32_16x16x32_bf16 v[112:115], v[178:181], v[186:189], v[112:115]
	v_mfma_f32_16x16x32_bf16 v[100:103], v[170:173], v[194:197], v[100:103]
	v_mfma_f32_16x16x32_bf16 v[96:99], v[178:181], v[194:197], v[96:99]
	v_mfma_f32_16x16x32_bf16 v[84:87], v[170:173], v[202:205], v[84:87]
	v_mfma_f32_16x16x32_bf16 v[80:83], v[178:181], v[202:205], v[80:83]
	v_mfma_f32_16x16x32_bf16 v[68:71], v[170:173], v[210:213], v[68:71]
	v_mfma_f32_16x16x32_bf16 v[64:67], v[178:181], v[210:213], v[64:67]
	v_mfma_f32_16x16x32_bf16 v[116:119], v[174:177], v[190:193], v[116:119]
	v_mfma_f32_16x16x32_bf16 v[112:115], v[182:185], v[190:193], v[112:115]
	v_mfma_f32_16x16x32_bf16 v[100:103], v[174:177], v[198:201], v[100:103]
	v_mfma_f32_16x16x32_bf16 v[96:99], v[182:185], v[198:201], v[96:99]
	v_mfma_f32_16x16x32_bf16 v[84:87], v[174:177], v[206:209], v[84:87]
	v_mfma_f32_16x16x32_bf16 v[80:83], v[182:185], v[206:209], v[80:83]
	v_mfma_f32_16x16x32_bf16 v[68:71], v[174:177], v[214:217], v[68:71]
	v_mfma_f32_16x16x32_bf16 v[64:67], v[182:185], v[214:217], v[64:67]
	s_setprio 0
	s_barrier
	s_add_i32 s26, s52, s9
	v_lshl_add_u64 v[166:167], v[166:167], 0, s[12:13]
	s_mov_b32 m0, s26
	ds_read_b128 v[186:189], v148 offset:49152
	ds_read_b128 v[190:193], v148 offset:50176
	ds_read_b128 v[194:197], v148 offset:51200
	ds_read_b128 v[198:201], v148 offset:52224
	ds_read_b128 v[202:205], v148 offset:53248
	ds_read_b128 v[206:209], v148 offset:54272
	ds_read_b128 v[210:213], v148 offset:55296
	ds_read_b128 v[214:217], v148 offset:56320
	global_load_lds_dwordx4 v[166:167], off
	s_add_i32 m0, s26, 0x2000
	s_add_u32 s24, s24, 0x80080
	v_lshl_add_u64 v[166:167], v[218:219], 0, s[12:13]
	s_addc_u32 s25, s25, 0
	s_add_i32 s26, s53, s9
	global_load_lds_dwordx4 v[166:167], off
	v_lshl_add_u64 v[166:167], s[24:25], 0, v[130:131]
	s_mov_b32 m0, s26
	s_nop 0
	global_load_lds_dwordx4 v[166:167], off
	v_lshl_add_u64 v[166:167], s[24:25], 0, v[128:129]
	s_add_i32 m0, s26, 0x2000
	s_nop 0
	global_load_lds_dwordx4 v[166:167], off
	v_lshl_add_u64 v[166:167], v[220:221], 0, s[12:13]
	s_mov_b32 m0, s39
	s_nop 0
	global_load_lds_dwordx4 v[166:167], off
	v_lshl_add_u64 v[166:167], v[222:223], 0, s[12:13]
	s_mov_b32 m0, s40
	s_nop 0
	global_load_lds_dwordx4 v[166:167], off
	s_waitcnt vmcnt(8)
	s_waitcnt lgkmcnt(0)
	s_barrier
	s_setprio 1
	s_waitcnt lgkmcnt(0)
	v_mfma_f32_16x16x32_bf16 v[60:63], v[150:153], v[186:189], v[60:63]
	v_mfma_f32_16x16x32_bf16 v[56:59], v[158:161], v[186:189], v[56:59]
	v_mfma_f32_16x16x32_bf16 v[44:47], v[150:153], v[194:197], v[44:47]
	s_add_i32 s51, s51, 2
	v_mfma_f32_16x16x32_bf16 v[40:43], v[158:161], v[194:197], v[40:43]
	s_add_u32 s22, s22, 0x100
	v_mfma_f32_16x16x32_bf16 v[28:31], v[150:153], v[202:205], v[28:31]
	s_addc_u32 s23, s23, 0
	v_mfma_f32_16x16x32_bf16 v[24:27], v[158:161], v[202:205], v[24:27]
	s_cmp_gt_u32 s51, 29
	v_mfma_f32_16x16x32_bf16 v[12:15], v[150:153], v[210:213], v[12:15]
	v_mfma_f32_16x16x32_bf16 v[8:11], v[158:161], v[210:213], v[8:11]
	v_mfma_f32_16x16x32_bf16 v[60:63], v[154:157], v[190:193], v[60:63]
	v_mfma_f32_16x16x32_bf16 v[56:59], v[162:165], v[190:193], v[56:59]
	v_mfma_f32_16x16x32_bf16 v[44:47], v[154:157], v[198:201], v[44:47]
	v_mfma_f32_16x16x32_bf16 v[40:43], v[162:165], v[198:201], v[40:43]
	v_mfma_f32_16x16x32_bf16 v[28:31], v[154:157], v[206:209], v[28:31]
	v_mfma_f32_16x16x32_bf16 v[24:27], v[162:165], v[206:209], v[24:27]
	v_mfma_f32_16x16x32_bf16 v[12:15], v[154:157], v[214:217], v[12:15]
	v_mfma_f32_16x16x32_bf16 v[8:11], v[162:165], v[214:217], v[8:11]
	s_setprio 0
	s_setprio 1
	v_mfma_f32_16x16x32_bf16 v[52:55], v[170:173], v[186:189], v[52:55]
	v_mfma_f32_16x16x32_bf16 v[48:51], v[178:181], v[186:189], v[48:51]
	v_mfma_f32_16x16x32_bf16 v[36:39], v[170:173], v[194:197], v[36:39]
	v_mfma_f32_16x16x32_bf16 v[32:35], v[178:181], v[194:197], v[32:35]
	v_mfma_f32_16x16x32_bf16 v[20:23], v[170:173], v[202:205], v[20:23]
	v_mfma_f32_16x16x32_bf16 v[16:19], v[178:181], v[202:205], v[16:19]
	v_mfma_f32_16x16x32_bf16 v[4:7], v[170:173], v[210:213], v[4:7]
	v_mfma_f32_16x16x32_bf16 v[0:3], v[178:181], v[210:213], v[0:3]
	v_mfma_f32_16x16x32_bf16 v[52:55], v[174:177], v[190:193], v[52:55]
	v_mfma_f32_16x16x32_bf16 v[48:51], v[182:185], v[190:193], v[48:51]
	v_mfma_f32_16x16x32_bf16 v[36:39], v[174:177], v[198:201], v[36:39]
	v_mfma_f32_16x16x32_bf16 v[32:35], v[182:185], v[198:201], v[32:35]
	v_mfma_f32_16x16x32_bf16 v[20:23], v[174:177], v[206:209], v[20:23]
	v_mfma_f32_16x16x32_bf16 v[16:19], v[182:185], v[206:209], v[16:19]
	v_mfma_f32_16x16x32_bf16 v[4:7], v[174:177], v[214:217], v[4:7]
	v_mfma_f32_16x16x32_bf16 v[0:3], v[182:185], v[214:217], v[0:3]
	s_setprio 0
	s_barrier
	s_cbranch_scc0 .LBB0_661
	s_add_u32 s22, s47, 0xffffff00
	s_addc_u32 s23, s48, -1
	s_andn2_b64 vcc, exec, s[4:5]
	s_cbranch_vccnz .LBB0_652
	v_mov_b32_e32 v0, 0
	s_mov_b32 s8, s14
	s_mov_b32 s6, s16
	s_mov_b64 s[10:11], s[20:21]
	s_mov_b32 s41, s46
	v_mov_b32_e32 v1, v0
	v_mov_b32_e32 v2, v0
	v_mov_b32_e32 v3, v0
	v_mov_b32_e32 v4, v0
	v_mov_b32_e32 v5, v0
	v_mov_b32_e32 v6, v0
	v_mov_b32_e32 v7, v0
	v_mov_b32_e32 v16, v0
	v_mov_b32_e32 v17, v0
	v_mov_b32_e32 v18, v0
	v_mov_b32_e32 v19, v0
	v_mov_b32_e32 v20, v0
	v_mov_b32_e32 v21, v0
	v_mov_b32_e32 v22, v0
	v_mov_b32_e32 v23, v0
	v_mov_b32_e32 v32, v0
	v_mov_b32_e32 v33, v0
	v_mov_b32_e32 v34, v0
	v_mov_b32_e32 v35, v0
	v_mov_b32_e32 v36, v0
	v_mov_b32_e32 v37, v0
	v_mov_b32_e32 v38, v0
	v_mov_b32_e32 v39, v0
	v_mov_b32_e32 v48, v0
	v_mov_b32_e32 v49, v0
	v_mov_b32_e32 v50, v0
	v_mov_b32_e32 v51, v0
	v_mov_b32_e32 v52, v0
	v_mov_b32_e32 v53, v0
	v_mov_b32_e32 v54, v0
	v_mov_b32_e32 v55, v0
	v_mov_b32_e32 v8, v0
	v_mov_b32_e32 v9, v0
	v_mov_b32_e32 v10, v0
	v_mov_b32_e32 v11, v0
	v_mov_b32_e32 v12, v0
	v_mov_b32_e32 v13, v0
	v_mov_b32_e32 v14, v0
	v_mov_b32_e32 v15, v0
	v_mov_b32_e32 v24, v0
	v_mov_b32_e32 v25, v0
	v_mov_b32_e32 v26, v0
	v_mov_b32_e32 v27, v0
	v_mov_b32_e32 v28, v0
	v_mov_b32_e32 v29, v0
	v_mov_b32_e32 v30, v0
	v_mov_b32_e32 v31, v0
	v_mov_b32_e32 v40, v0
	v_mov_b32_e32 v41, v0
	v_mov_b32_e32 v42, v0
	v_mov_b32_e32 v43, v0
	v_mov_b32_e32 v44, v0
	v_mov_b32_e32 v45, v0
	v_mov_b32_e32 v46, v0
	v_mov_b32_e32 v47, v0
	v_mov_b32_e32 v56, v0
	v_mov_b32_e32 v57, v0
	v_mov_b32_e32 v58, v0
	v_mov_b32_e32 v59, v0
	v_mov_b32_e32 v60, v0
	v_mov_b32_e32 v61, v0
	v_mov_b32_e32 v62, v0
	v_mov_b32_e32 v63, v0
	v_mov_b32_e32 v64, v0
	v_mov_b32_e32 v65, v0
	v_mov_b32_e32 v66, v0
	v_mov_b32_e32 v67, v0
	v_mov_b32_e32 v68, v0
	v_mov_b32_e32 v69, v0
	v_mov_b32_e32 v70, v0
	v_mov_b32_e32 v71, v0
	v_mov_b32_e32 v80, v0
	v_mov_b32_e32 v81, v0
	v_mov_b32_e32 v82, v0
	v_mov_b32_e32 v83, v0
	v_mov_b32_e32 v84, v0
	v_mov_b32_e32 v85, v0
	v_mov_b32_e32 v86, v0
	v_mov_b32_e32 v87, v0
	v_mov_b32_e32 v96, v0
	v_mov_b32_e32 v97, v0
	v_mov_b32_e32 v98, v0
	v_mov_b32_e32 v99, v0
	v_mov_b32_e32 v100, v0
	v_mov_b32_e32 v101, v0
	v_mov_b32_e32 v102, v0
	v_mov_b32_e32 v103, v0
	v_mov_b32_e32 v112, v0
	v_mov_b32_e32 v113, v0
	v_mov_b32_e32 v114, v0
	v_mov_b32_e32 v115, v0
	v_mov_b32_e32 v116, v0
	v_mov_b32_e32 v117, v0
	v_mov_b32_e32 v118, v0
	v_mov_b32_e32 v119, v0
	v_mov_b32_e32 v72, v0
	v_mov_b32_e32 v73, v0
	v_mov_b32_e32 v74, v0
	v_mov_b32_e32 v75, v0
	v_mov_b32_e32 v76, v0
	v_mov_b32_e32 v77, v0
	v_mov_b32_e32 v78, v0
	v_mov_b32_e32 v79, v0
	v_mov_b32_e32 v88, v0
	v_mov_b32_e32 v89, v0
	v_mov_b32_e32 v90, v0
	v_mov_b32_e32 v91, v0
	v_mov_b32_e32 v92, v0
	v_mov_b32_e32 v93, v0
	v_mov_b32_e32 v94, v0
	v_mov_b32_e32 v95, v0
	v_mov_b32_e32 v104, v0
	v_mov_b32_e32 v105, v0
	v_mov_b32_e32 v106, v0
	v_mov_b32_e32 v107, v0
	v_mov_b32_e32 v108, v0
	v_mov_b32_e32 v109, v0
	v_mov_b32_e32 v110, v0
	v_mov_b32_e32 v111, v0
	v_mov_b32_e32 v120, v0
	v_mov_b32_e32 v121, v0
	v_mov_b32_e32 v122, v0
	v_mov_b32_e32 v123, v0
	v_mov_b32_e32 v124, v0
	v_mov_b32_e32 v125, v0
	v_mov_b32_e32 v126, v0
	v_mov_b32_e32 v127, v0
	s_andn2_b64 vcc, exec, s[0:1]
	s_cbranch_vccnz .LBB0_653
